# stack8 + counted waits in the G3 unit loop: the top barrier waits only for the tile DMA (vmcnt 10), query fragments waited at first use, gate/norm vectors before the next-tile DMA
# baseline (speedup 1.0000x reference)
; __device__ __forceinline__ void gla_g3(LAS unsigned char* lds, const bf16_t* P, const bf16_t* VAT, const bf16_t* DS, const float* BC, const float* gn, bf16_t* MIX) {
;     ...
;         const int c = uid & 31, h = (uid >> 5) & 3, bl = uid >> 7;
;         const size_t row0 = (size_t)bl * SEQ + c * 64, qrow = row0 + iq;
;         bf16x8 qraw[2]; f32x4 gvv[4]; u32x2 rvv[4];
; #pragma unroll
;         for (int s2 = 0; s2 < 2; ++s2) qraw[s2] = *(const bf16x8*)(P + qrow * 2048 + h * 64 + 32 * s2 + 8 * g);
; #pragma unroll
;         for (int mb = 0; mb < 4; ++mb) { const int cc = h * 128 + 16 * (4 * dvh + mb) + 4 * g; gvv[mb] = *(const f32x4*)(gn + cc); rvv[mb] = *(const u32x2*)(P + qrow * 2048 + 512 + cc); }
;         asm volatile("s_waitcnt vmcnt(0)" ::: "memory");
;         __syncthreads();
.LBB0_629:
	s_ashr_i32 s0, s94, 7
	s_ashr_i32 s1, s0, 31
	s_lshl_b32 s2, s94, 6
	s_lshl_b64 s[0:1], s[0:1], 11
	s_and_b32 s2, s2, 0x7c0
	s_or_b32 s0, s0, s2
	v_mov_b32_e32 v49, s1
	v_or_b32_e32 v48, s0, v36
	v_lshlrev_b64 v[0:1], 12, v[48:49]
	s_lshl_b32 s0, s94, 2
	v_lshl_add_u64 v[0:1], s[24:25], 0, v[0:1]
	s_and_b32 s2, s0, 0x180
	v_lshl_add_u64 v[2:3], v[0:1], 0, s[2:3]
	v_lshl_add_u64 v[2:3], v[2:3], 0, v[190:191]
	global_load_dwordx4 v[20:23], v[2:3], off
	global_load_dwordx4 v[16:19], v[2:3], off offset:64
	v_add_u32_e32 v44, s2, v50
	v_ashrrev_i32_e32 v45, 31, v44
	v_lshl_add_u64 v[2:3], v[44:45], 2, s[80:81]
	v_lshl_add_u64 v[24:25], v[44:45], 1, v[0:1]
	global_load_dwordx4 v[12:15], v[2:3], off
	global_load_dwordx2 v[46:47], v[24:25], off offset:1024
	global_load_dwordx4 v[8:11], v[2:3], off offset:64
	global_load_dwordx2 v[42:43], v[24:25], off offset:1056
	global_load_dwordx4 v[4:7], v[2:3], off offset:128
	global_load_dwordx2 v[40:41], v[24:25], off offset:1088
	s_nop 0
	global_load_dwordx4 v[0:3], v[2:3], off offset:192
	s_nop 0
	global_load_dwordx2 v[38:39], v[24:25], off offset:1120
	v_add_u32_e32 v24, 0, v51
	s_waitcnt vmcnt(10)
	s_waitcnt vmcnt(10) lgkmcnt(0)
	s_barrier
	s_add_i32 s98, s94, s92
	s_cmpk_gt_i32 s98, 0xbff
	s_cbranch_scc1 .Lg3_touch_done
	v_lshrrev_b32_e32 v100, 6, v250
	v_and_b32_e32 v101, 63, v250
	s_mov_b32 m0, 0x20000
	v_mov_b32_e32 v105, 0
	v_readfirstlane_b32 s99, v100
	v_and_b32_e32 v103, 3, v100
	v_lshlrev_b32_e32 v104, 7, v101
	v_lshl_add_u32 v104, v103, 13, v104
	s_lshl_b32 s100, s98, 15
	v_add_u32_e32 v104, s100, v104
	s_cmp_lt_u32 s99, 4
	s_cbranch_scc0 .Lg3_touch_bc
	v_lshl_add_u64 v[106:107], s[36:37], 0, v[104:105]
	s_branch .Lg3_touch_c

; #define LAS __attribute__((address_space(3)))
; __device__ __forceinline__ void gla_g3(LAS unsigned char* lds, const bf16_t* P, const bf16_t* VAT, const bf16_t* DS, const float* BC, const float* gn, bf16_t* MIX) {
;     ...
;             const int j = 8 * wv + (lane >> 3), ch = lane & 7;
;             const bf16x8 kr = *(const LAS bf16x8*)(lds + G3_KRAW + (j * 9 + ch) * 16);
;             const LAS float* tf = (const LAS float*)(lds + G3_TBF + j * 272 + ch * 32); const LAS float* tb = (const LAS float*)(lds + G3_TBB + j * 272 + ch * 32);
;             f32x4 a0 = *(const LAS f32x4*)tf, a1 = *(const LAS f32x4*)(tf + 4), b0 = *(const LAS f32x4*)tb, b1 = *(const LAS f32x4*)(tb + 4);
; #pragma unroll
;             for (int q = 0; q < 4; ++q) { a0[q] = __builtin_amdgcn_exp2f(-a0[q]); a1[q] = __builtin_amdgcn_exp2f(-a1[q]); b0[q] = __builtin_amdgcn_exp2f(-b0[q]); b1[q] = __builtin_amdgcn_exp2f(-b1[q]); }
;             *(LAS bf16x8*)(lds + G3_KIF + (j * 9 + ch) * 16) = scale8(kr, a0, a1); *(LAS bf16x8*)(lds + G3_KIB + (j * 9 + ch) * 16) = scale8(kr, b0, b1);
;         }
;         bf16x8 qdf[2], qdb[2];
; #pragma unroll
;         for (int s2 = 0; s2 < 2; ++s2) {
;             const LAS float* tf = (const LAS float*)(lds + G3_TBF + iq * 272 + (32 * s2 + 8 * g) * 4); const LAS float* tb = (const LAS float*)(lds + G3_TBB + iq * 272 + (32 * s2 + 8 * g) * 4);
;             f32x4 a0 = *(const LAS f32x4*)tf, a1 = *(const LAS f32x4*)(tf + 4), b0 = *(const LAS f32x4*)tb, b1 = *(const LAS f32x4*)(tb + 4);
; #pragma unroll
;             for (int q = 0; q < 4; ++q) { a0[q] = __builtin_amdgcn_exp2f(a0[q]); a1[q] = __builtin_amdgcn_exp2f(a1[q]); b0[q] = __builtin_amdgcn_exp2f(b0[q]); b1[q] = __builtin_amdgcn_exp2f(b1[q]); }
;             qdf[s2] = scale8(qraw[s2], a0, a1); qdb[s2] = scale8(qraw[s2], b0, b1);
;         }
;         __syncthreads();
.Lg3_touch_done:
	ds_read_b128 v[24:27], v24
	ds_read_b128 v[28:31], v57 offset:64512
	ds_read_b128 v[32:35], v57 offset:64528
	ds_read_b128 v[70:73], v58
	ds_read_b128 v[74:77], v58 offset:16
	s_waitcnt lgkmcnt(4)
	v_lshlrev_b32_e32 v78, 16, v24
	s_waitcnt lgkmcnt(3)
	v_exp_f32_e64 v28, -v28
	v_exp_f32_e64 v29, -v29
	v_exp_f32_e64 v30, -v30
	v_exp_f32_e64 v31, -v31
	v_and_b32_e32 v79, 0xffff0000, v24
	s_waitcnt lgkmcnt(2)
	v_exp_f32_e64 v32, -v32
	v_exp_f32_e64 v33, -v33
	v_pk_mul_f32 v[28:29], v[28:29], v[78:79]
	v_exp_f32_e64 v34, -v34
	v_cvt_pk_bf16_f32 v24, v28, v29
	v_lshlrev_b32_e32 v28, 16, v25
	v_and_b32_e32 v29, 0xffff0000, v25
	v_exp_f32_e64 v35, -v35
	v_pk_mul_f32 v[30:31], v[30:31], v[28:29]
	s_waitcnt lgkmcnt(1)
	v_exp_f32_e64 v70, -v70
	v_cvt_pk_bf16_f32 v25, v30, v31
	v_lshlrev_b32_e32 v30, 16, v26
	v_and_b32_e32 v31, 0xffff0000, v26
	v_exp_f32_e64 v71, -v71
	v_exp_f32_e64 v72, -v72
	v_exp_f32_e64 v73, -v73
	v_pk_mul_f32 v[32:33], v[32:33], v[30:31]
	s_waitcnt lgkmcnt(0)
	v_exp_f32_e64 v74, -v74
	v_exp_f32_e64 v75, -v75
	v_exp_f32_e64 v76, -v76
	v_exp_f32_e64 v77, -v77
	v_cvt_pk_bf16_f32 v26, v32, v33
	v_lshlrev_b32_e32 v32, 16, v27
	v_and_b32_e32 v33, 0xffff0000, v27
	v_pk_mul_f32 v[34:35], v[34:35], v[32:33]
	v_readlane_b32 s0, v254, 34
	v_cvt_pk_bf16_f32 v27, v34, v35
	v_add_u32_e32 v34, s35, v51
	ds_write_b128 v34, v[24:27]
	v_pk_mul_f32 v[24:25], v[70:71], v[78:79]
	v_pk_mul_f32 v[26:27], v[72:73], v[28:29]
	v_cvt_pk_bf16_f32 v24, v24, v25
	v_cvt_pk_bf16_f32 v25, v26, v27
	v_pk_mul_f32 v[26:27], v[74:75], v[30:31]
	v_pk_mul_f32 v[28:29], v[76:77], v[32:33]
	v_cvt_pk_bf16_f32 v26, v26, v27
	v_cvt_pk_bf16_f32 v27, v28, v29
	v_add_u32_e32 v28, s0, v51
	ds_write_b128 v28, v[24:27]
	ds_read_b128 v[24:27], v59 offset:64512
	ds_read_b128 v[28:31], v59 offset:64528
	ds_read_b128 v[32:35], v60
	ds_read_b128 v[70:73], v60 offset:16
	v_add_u32_e32 v69, s35, v53
	s_waitcnt lgkmcnt(3)
	v_exp_f32_e32 v24, v24
	v_exp_f32_e32 v25, v25
	s_waitcnt lgkmcnt(1)
	v_exp_f32_e32 v32, v32
	v_exp_f32_e32 v33, v33
	v_exp_f32_e32 v26, v26
	v_exp_f32_e32 v27, v27
	v_exp_f32_e32 v34, v34
	v_exp_f32_e32 v35, v35
	v_exp_f32_e32 v28, v28
	v_exp_f32_e32 v29, v29
	s_waitcnt lgkmcnt(0)
	v_exp_f32_e32 v70, v70
	v_exp_f32_e32 v71, v71
	v_exp_f32_e32 v30, v30
	v_exp_f32_e32 v72, v72
	v_exp_f32_e32 v31, v31
	v_exp_f32_e32 v73, v73
	v_add_u32_e32 v86, s0, v54
	v_add_u32_e32 v90, s0, v56
	s_waitcnt vmcnt(8)
	v_lshlrev_b32_e32 v74, 16, v20
	v_and_b32_e32 v75, 0xffff0000, v20
	v_pk_mul_f32 v[24:25], v[24:25], v[74:75]
	v_lshlrev_b32_e32 v78, 16, v16
	v_cvt_pk_bf16_f32 v20, v24, v25
	v_pk_mul_f32 v[24:25], v[32:33], v[74:75]
	v_lshlrev_b32_e32 v32, 16, v21
	v_and_b32_e32 v33, 0xffff0000, v21
	v_pk_mul_f32 v[26:27], v[26:27], v[32:33]
	v_cvt_pk_bf16_f32 v24, v24, v25
	v_cvt_pk_bf16_f32 v21, v26, v27
	v_pk_mul_f32 v[26:27], v[34:35], v[32:33]
	v_and_b32_e32 v79, 0xffff0000, v16
	v_cvt_pk_bf16_f32 v25, v26, v27
	v_lshlrev_b32_e32 v26, 16, v22
	v_and_b32_e32 v27, 0xffff0000, v22
	v_pk_mul_f32 v[28:29], v[28:29], v[26:27]
	v_pk_mul_f32 v[26:27], v[70:71], v[26:27]
	v_cvt_pk_bf16_f32 v22, v28, v29
	v_lshlrev_b32_e32 v28, 16, v23
	v_and_b32_e32 v29, 0xffff0000, v23
	v_pk_mul_f32 v[30:31], v[30:31], v[28:29]
	v_pk_mul_f32 v[28:29], v[72:73], v[28:29]
	v_cvt_pk_bf16_f32 v26, v26, v27
	v_cvt_pk_bf16_f32 v23, v30, v31
	v_cvt_pk_bf16_f32 v27, v28, v29
	ds_read_b128 v[28:31], v59 offset:64640
	ds_read_b128 v[32:35], v59 offset:64656
	ds_read_b128 v[70:73], v60 offset:128
	ds_read_b128 v[74:77], v60 offset:144
	s_waitcnt lgkmcnt(0)
	v_exp_f32_e32 v28, v28
	v_exp_f32_e32 v29, v29
	v_exp_f32_e32 v70, v70
	v_exp_f32_e32 v71, v71
	v_exp_f32_e32 v30, v30
	v_exp_f32_e32 v31, v31
	v_exp_f32_e32 v72, v72
	v_exp_f32_e32 v73, v73
	v_exp_f32_e32 v32, v32
	v_exp_f32_e32 v74, v74
	v_exp_f32_e32 v33, v33
	v_exp_f32_e32 v75, v75
	v_pk_mul_f32 v[70:71], v[70:71], v[78:79]
	v_exp_f32_e32 v34, v34
	v_cvt_pk_bf16_f32 v16, v70, v71
	v_lshlrev_b32_e32 v70, 16, v17
	v_and_b32_e32 v71, 0xffff0000, v17
	v_exp_f32_e32 v76, v76
	v_exp_f32_e32 v35, v35
	v_exp_f32_e32 v77, v77
	v_pk_mul_f32 v[28:29], v[28:29], v[78:79]
	v_pk_mul_f32 v[30:31], v[30:31], v[70:71]
	v_cvt_pk_bf16_f32 v28, v28, v29
	v_cvt_pk_bf16_f32 v29, v30, v31
	v_pk_mul_f32 v[30:31], v[72:73], v[70:71]
	v_lshlrev_b32_e32 v70, 16, v18
	v_and_b32_e32 v71, 0xffff0000, v18
	v_cvt_pk_bf16_f32 v17, v30, v31
	v_pk_mul_f32 v[30:31], v[32:33], v[70:71]
	v_pk_mul_f32 v[32:33], v[74:75], v[70:71]
	v_cvt_pk_bf16_f32 v30, v30, v31
	v_cvt_pk_bf16_f32 v18, v32, v33
	v_lshlrev_b32_e32 v32, 16, v19
	v_and_b32_e32 v33, 0xffff0000, v19
	v_pk_mul_f32 v[34:35], v[34:35], v[32:33]
	v_pk_mul_f32 v[32:33], v[76:77], v[32:33]
	v_cvt_pk_bf16_f32 v31, v34, v35
	v_cvt_pk_bf16_f32 v19, v32, v33
	s_barrier
; #define LAS __attribute__((address_space(3)))
; __device__ __forceinline__ u32x4 pack8(const f32x4 a, const f32x4 b) { u32x4 w; w.x = cvt_pk_bf16(a[0], a[1]); w.y = cvt_pk_bf16(a[2], a[3]); w.z = cvt_pk_bf16(b[0], b[1]); w.w = cvt_pk_bf16(b[2], b[3]); return w; }
; __device__ __forceinline__ f32x4 mfma16(bf16x8 a, bf16x8 b, f32x4 c) { return __builtin_amdgcn_mfma_f32_16x16x32_bf16(a, b, c, 0, 0, 0); }
; __device__ __forceinline__ void gla_g3(LAS unsigned char* lds, const bf16_t* P, const bf16_t* VAT, const bf16_t* DS, const float* BC, const float* gn, bf16_t* MIX) {
;     ...
;         bf16x8 pfrag[2];
; #pragma unroll
;         for (int t = 0; t < 2; ++t) {
;             f32x4 sf[2], sv[2];
; #pragma unroll
;             for (int u = 0; u < 2; ++u) {
;                 const int j = 32 * t + 8 * (fr >> 2) + 4 * u + (fr & 3);
;                 sf[u] = (f32x4){0.f, 0.f, 0.f, 0.f}; sv[u] = (f32x4){0.f, 0.f, 0.f, 0.f};
; #pragma unroll
;                 for (int s2 = 0; s2 < 2; ++s2) {
;                     sf[u] = mfma16(*(const LAS bf16x8*)(lds + G3_KIF + (j * 9 + 4 * s2 + g) * 16), qdf[s2], sf[u]);
;                     sv[u] = mfma16(*(const LAS bf16x8*)(lds + G3_KIB + (j * 9 + 4 * s2 + g) * 16), qdb[s2], sv[u]);
;                 }
;             }
;             f32x4 p0, p1;
; #pragma unroll
;             for (int ii = 0; ii < 4; ++ii) { const int j0 = 32 * t + 8 * g + ii, j1 = j0 + 4; p0[ii] = (j0 <= iq) ? sf[0][ii] : sv[0][ii]; p1[ii] = (j1 <= iq) ? sf[1][ii] : sv[1][ii]; }
;             pfrag[t] = __builtin_bit_cast(bf16x8, pack8(p0, p1));
;         }
;         f32x4 o[4];
; #pragma unroll
;         for (int mb = 0; mb < 4; ++mb) o[mb] = (f32x4){0.f, 0.f, 0.f, 0.f};
; #pragma unroll
;         for (int t = 0; t < 2; ++t)
; #pragma unroll
;             for (int mb = 0; mb < 4; ++mb) o[mb] = mfma16(*(const LAS bf16x8*)(lds + G3_VT + ((16 * (4 * dvh + mb) + fr) * 9 + 4 * t + g) * 16), pfrag[t], o[mb]);
	ds_read_b128 v[32:35], v69
	ds_read_b128 v[74:77], v69 offset:64
	v_add_u32_e32 v78, s0, v53
	s_waitcnt lgkmcnt(1)
	v_mfma_f32_16x16x32_bf16 v[32:35], v[32:35], v[20:23], 0
	ds_read_b128 v[70:73], v78
	v_add_u32_e32 v69, s35, v54
	ds_read_b128 v[82:85], v69 offset:64
	s_waitcnt lgkmcnt(2)
	v_mfma_f32_16x16x32_bf16 v[32:35], v[74:77], v[28:31], v[32:35]
	ds_read_b128 v[74:77], v78 offset:64
	ds_read_b128 v[78:81], v86
	s_waitcnt lgkmcnt(3)
	v_mfma_f32_16x16x32_bf16 v[70:73], v[70:73], v[24:27], 0
	s_waitcnt lgkmcnt(1)
	v_mfma_f32_16x16x32_bf16 v[70:73], v[74:77], v[16:19], v[70:73]
	ds_read_b128 v[74:77], v69
	s_waitcnt lgkmcnt(0)
	v_mfma_f32_16x16x32_bf16 v[74:77], v[74:77], v[20:23], 0
	s_nop 4
	v_cndmask_b32_e64 v32, v32, v70, s[42:43]
	v_cndmask_b32_e64 v33, v71, v33, s[46:47]
	v_cndmask_b32_e64 v34, v34, v72, s[50:51]
	v_mfma_f32_16x16x32_bf16 v[74:77], v[82:85], v[28:31], v[74:77]
	ds_read_b128 v[82:85], v86 offset:64
	v_cndmask_b32_e64 v35, v35, v73, s[54:55]
	v_cvt_pk_bf16_f32 v32, v32, v33
	v_mfma_f32_16x16x32_bf16 v[78:81], v[78:81], v[24:27], 0
	v_cvt_pk_bf16_f32 v33, v34, v35
	s_waitcnt lgkmcnt(0)
	v_mfma_f32_16x16x32_bf16 v[78:81], v[82:85], v[16:19], v[78:81]
	v_add_u32_e32 v82, s0, v55
	s_nop 6
	v_cndmask_b32_e64 v69, v74, v78, s[44:45]
	v_cndmask_b32_e64 v70, v75, v79, s[48:49]
	v_cndmask_b32_e64 v71, v76, v80, s[52:53]
	v_cndmask_b32_e64 v72, v77, v81, s[56:57]
	v_cvt_pk_bf16_f32 v34, v69, v70
	v_add_u32_e32 v69, s35, v55
	v_cvt_pk_bf16_f32 v35, v71, v72
	ds_read_b128 v[70:73], v69
	ds_read_b128 v[78:81], v69 offset:64
	s_waitcnt lgkmcnt(1)
	v_mfma_f32_16x16x32_bf16 v[70:73], v[70:73], v[20:23], 0
	ds_read_b128 v[74:77], v82
	v_add_u32_e32 v69, s35, v56
	ds_read_b128 v[86:89], v69 offset:64
	s_waitcnt lgkmcnt(2)
	v_mfma_f32_16x16x32_bf16 v[70:73], v[78:81], v[28:31], v[70:73]
	ds_read_b128 v[78:81], v82 offset:64
	ds_read_b128 v[82:85], v90
	s_waitcnt lgkmcnt(3)
	v_mfma_f32_16x16x32_bf16 v[74:77], v[74:77], v[24:27], 0
	s_waitcnt lgkmcnt(1)
	v_mfma_f32_16x16x32_bf16 v[74:77], v[78:81], v[16:19], v[74:77]
	ds_read_b128 v[78:81], v69
	s_waitcnt lgkmcnt(0)
	v_mfma_f32_16x16x32_bf16 v[78:81], v[78:81], v[20:23], 0
	s_nop 4
	v_cndmask_b32_e64 v69, v70, v74, s[58:59]
	v_cndmask_b32_e64 v70, v71, v75, s[62:63]
	v_cndmask_b32_e64 v71, v72, v76, s[66:67]
	v_mfma_f32_16x16x32_bf16 v[78:81], v[86:89], v[28:31], v[78:81]
	ds_read_b128 v[86:89], v90 offset:64
	v_cndmask_b32_e64 v72, v73, v77, s[70:71]
	v_cvt_pk_bf16_f32 v71, v71, v72
	v_mfma_f32_16x16x32_bf16 v[82:85], v[82:85], v[24:27], 0
	v_cvt_pk_bf16_f32 v70, v69, v70
	s_waitcnt lgkmcnt(0)
	v_mfma_f32_16x16x32_bf16 v[82:85], v[86:89], v[16:19], v[82:85]
	ds_read_b128 v[86:89], v64 offset:9216
	s_nop 6
	v_cndmask_b32_e64 v74, v78, v82, s[60:61]
	v_cndmask_b32_e64 v75, v79, v83, s[64:65]
	v_cndmask_b32_e64 v76, v80, v84, s[68:69]
	v_cndmask_b32_e64 v73, v81, v85, s[72:73]
	v_cvt_pk_bf16_f32 v72, v74, v75
	v_cvt_pk_bf16_f32 v73, v76, v73
	ds_read_b128 v[74:77], v61 offset:9216
	ds_read_b128 v[78:81], v62 offset:9216
	ds_read_b128 v[82:85], v63 offset:9216
	s_waitcnt lgkmcnt(2)
	v_mfma_f32_16x16x32_bf16 v[74:77], v[74:77], v[32:35], 0
	s_waitcnt lgkmcnt(1)
	v_mfma_f32_16x16x32_bf16 v[78:81], v[78:81], v[32:35], 0
	s_waitcnt lgkmcnt(0)
	v_mfma_f32_16x16x32_bf16 v[82:85], v[82:85], v[32:35], 0
	v_mfma_f32_16x16x32_bf16 v[32:35], v[86:89], v[32:35], 0
	ds_read_b128 v[86:89], v65 offset:9216
	s_waitcnt lgkmcnt(0)
	v_mfma_f32_16x16x32_bf16 v[74:77], v[86:89], v[70:73], v[74:77]
	ds_read_b128 v[86:89], v66 offset:9216
	s_waitcnt lgkmcnt(0)
	v_mfma_f32_16x16x32_bf16 v[78:81], v[86:89], v[70:73], v[78:81]
	ds_read_b128 v[86:89], v67 offset:9216
	s_waitcnt lgkmcnt(0)
	v_mfma_f32_16x16x32_bf16 v[82:85], v[86:89], v[70:73], v[82:85]
	ds_read_b128 v[86:89], v68 offset:9216
	s_waitcnt lgkmcnt(0)
	v_mfma_f32_16x16x32_bf16 v[32:35], v[86:89], v[70:73], v[32:35]
	ds_read_b128 v[70:73], v61 offset:27648
	s_waitcnt lgkmcnt(0)
; #define LAS __attribute__((address_space(3)))
; __device__ __forceinline__ f32x4 mfma16(bf16x8 a, bf16x8 b, f32x4 c) { return __builtin_amdgcn_mfma_f32_16x16x32_bf16(a, b, c, 0, 0, 0); }
; __device__ __forceinline__ void g3_dma_unit(LAS unsigned char* lds, const bf16_t* P, const bf16_t* VAT, const bf16_t* DS, const float* BC, int uid, int wv, int lane) {
;     const int c = uid & 31, h = (uid >> 5) & 3, bl = uid >> 7;
;     const size_t row0 = (size_t)bl * SEQ + c * 64;
;     g3_dma_tile(lds + G3_KRAW, (const unsigned char*)(P + row0 * 2048 + 256 + h * 64), 4096, 8, 9, wv, lane);
; __device__ __forceinline__ void gla_g3(LAS unsigned char* lds, const bf16_t* P, const bf16_t* VAT, const bf16_t* DS, const float* BC, const float* gn, bf16_t* MIX) {
;     ...
; #pragma unroll
;         for (int s2 = 0; s2 < 2; ++s2)
; #pragma unroll
;             for (int mb = 0; mb < 4; ++mb) {
;                 o[mb] = mfma16(*(const LAS bf16x8*)(lds + G3_SF + ((16 * (4 * dvh + mb) + fr) * 9 + 4 * s2 + g) * 16), qdf[s2], o[mb]);
;                 o[mb] = mfma16(*(const LAS bf16x8*)(lds + G3_SB + ((16 * (4 * dvh + mb) + fr) * 9 + 4 * s2 + g) * 16), qdb[s2], o[mb]);
;             }
;         float ss = 0.f;
; #pragma unroll
;         for (int mb = 0; mb < 4; ++mb) ss += (o[mb][0] * o[mb][0] + o[mb][1] * o[mb][1]) + (o[mb][2] * o[mb][2] + o[mb][3] * o[mb][3]);
;         ss += __shfl_xor(ss, 16); ss += __shfl_xor(ss, 32);
;         LAS float* red = (LAS float*)(lds + G3_RED);
;         if (g == 0) red[iq * 2 + dvh] = ss;
;         __syncthreads();
;         if (uid + (int)gridDim.x < nun) g3_dma_unit(lds, P, VAT, DS, BC, uid + (int)gridDim.x, wv, lane);
;         const float rstd = rsqrtf((red[iq * 2] + red[iq * 2 + 1]) * (1.0f / 128.0f) + LN_EPS);
	v_mfma_f32_16x16x32_bf16 v[70:73], v[70:73], v[20:23], v[74:77]
	s_nop 2
	ds_read_b128 v[74:77], v61 offset:46080
	s_waitcnt lgkmcnt(0)
	v_mfma_f32_16x16x32_bf16 v[70:73], v[74:77], v[24:27], v[70:73]
	ds_read_b128 v[74:77], v62 offset:27648
	s_waitcnt lgkmcnt(0)
	v_mfma_f32_16x16x32_bf16 v[74:77], v[74:77], v[20:23], v[78:81]
	s_nop 2
	ds_read_b128 v[78:81], v62 offset:46080
	s_waitcnt lgkmcnt(0)
	v_mfma_f32_16x16x32_bf16 v[74:77], v[78:81], v[24:27], v[74:77]
	ds_read_b128 v[78:81], v63 offset:27648
	s_waitcnt lgkmcnt(0)
	v_mfma_f32_16x16x32_bf16 v[78:81], v[78:81], v[20:23], v[82:85]
	s_nop 2
	ds_read_b128 v[82:85], v63 offset:46080
	s_waitcnt lgkmcnt(0)
	v_mfma_f32_16x16x32_bf16 v[78:81], v[82:85], v[24:27], v[78:81]
	ds_read_b128 v[82:85], v64 offset:27648
	s_waitcnt lgkmcnt(0)
	v_mfma_f32_16x16x32_bf16 v[20:23], v[82:85], v[20:23], v[32:35]
	s_nop 2
	ds_read_b128 v[32:35], v64 offset:46080
	s_waitcnt lgkmcnt(0)
	v_mfma_f32_16x16x32_bf16 v[82:85], v[32:35], v[24:27], v[20:23]
	s_nop 2
	ds_read_b128 v[20:23], v65 offset:27648
	ds_read_b128 v[24:27], v65 offset:46080
	s_waitcnt lgkmcnt(1)
	v_mfma_f32_16x16x32_bf16 v[20:23], v[20:23], v[28:31], v[70:73]
	s_nop 2
	ds_read_b128 v[70:73], v67 offset:46080
	s_waitcnt lgkmcnt(1)
	v_mfma_f32_16x16x32_bf16 v[32:35], v[24:27], v[16:19], v[20:23]
	ds_read_b128 v[24:27], v66 offset:46080
	s_nop 1
	ds_read_b128 v[20:23], v66 offset:27648
	s_waitcnt lgkmcnt(0)
	v_mfma_f32_16x16x32_bf16 v[20:23], v[20:23], v[28:31], v[74:77]
	v_mfma_f32_16x16x32_bf16 v[24:27], v[24:27], v[16:19], v[20:23]
	s_nop 6
	ds_read_b128 v[20:23], v67 offset:27648
	s_waitcnt lgkmcnt(0)
	v_mfma_f32_16x16x32_bf16 v[20:23], v[20:23], v[28:31], v[78:81]
	v_mfma_f32_16x16x32_bf16 v[20:23], v[70:73], v[16:19], v[20:23]
	ds_read_b128 v[70:73], v68 offset:27648
	s_waitcnt lgkmcnt(0)
	v_mfma_f32_16x16x32_bf16 v[28:31], v[70:73], v[28:31], v[82:85]
	ds_read_b128 v[70:73], v68 offset:46080
	s_waitcnt lgkmcnt(0)
	v_mfma_f32_16x16x32_bf16 v[16:19], v[70:73], v[16:19], v[28:31]
	s_nop 4
	v_mul_f32_e32 v28, v33, v33
	v_mul_f32_e32 v29, v35, v35
	v_fmac_f32_e32 v28, v32, v32
	v_fmac_f32_e32 v29, v34, v34
	v_add_f32_e32 v28, v28, v29
	v_mul_f32_e32 v29, v25, v25
	v_mul_f32_e32 v30, v27, v27
	v_fmac_f32_e32 v29, v24, v24
	v_fmac_f32_e32 v30, v26, v26
	v_add_f32_e32 v29, v29, v30
	v_add_f32_e32 v28, v28, v29
	v_mul_f32_e32 v29, v21, v21
	v_mul_f32_e32 v30, v23, v23
	v_fmac_f32_e32 v29, v20, v20
	v_fmac_f32_e32 v30, v22, v22
	v_add_f32_e32 v29, v29, v30
	v_add_f32_e32 v28, v28, v29
	v_mul_f32_e32 v29, v17, v17
	v_mul_f32_e32 v30, v19, v19
	v_fmac_f32_e32 v29, v16, v16
	v_fmac_f32_e32 v30, v18, v18
	v_add_f32_e32 v29, v29, v30
	v_add_f32_e32 v28, v28, v29
	v_xor_b32_e32 v29, 16, v231
	v_cmp_lt_i32_e32 vcc, v29, v232
	s_nop 1
	v_cndmask_b32_e32 v29, v231, v29, vcc
	v_lshlrev_b32_e32 v29, 2, v29
	ds_bpermute_b32 v29, v29, v28
	s_waitcnt lgkmcnt(0)
	v_add_f32_e32 v28, v28, v29
	v_xor_b32_e32 v29, 32, v231
	v_cmp_lt_i32_e32 vcc, v29, v232
	s_nop 1
	v_cndmask_b32_e32 v29, v231, v29, vcc
	v_lshlrev_b32_e32 v29, 2, v29
	ds_bpermute_b32 v29, v29, v28
	s_and_saveexec_b64 s[0:1], s[40:41]
	s_cbranch_execz .LBB0_631
	s_waitcnt lgkmcnt(0)
	v_add_f32_e32 v28, v28, v29
	v_add_u32_e32 v29, s16, v52
	ds_write_b32 v29, v28
.LBB0_631:
	s_or_b64 exec, exec, s[0:1]
	s_add_i32 s94, s94, s92
	s_cmpk_gt_i32 s94, 0xbff
	s_cselect_b64 s[10:11], -1, 0
	s_and_b64 vcc, exec, s[10:11]
	s_waitcnt vmcnt(0) lgkmcnt(0)
	s_barrier
	s_cbranch_vccnz .LBB0_628
	s_lshl_b32 s0, s94, 6
	s_bfe_u32 s2, s94, 0x20005
	s_ashr_i32 s14, s94, 7
	s_andn2_b64 vcc, exec, s[26:27]
	s_and_b32 s77, s0, 0x7c0
	s_mov_b64 s[82:83], 0x200
	s_cbranch_vccnz .LBB0_635
	s_ashr_i32 s15, s14, 31
	s_lshl_b64 s[0:1], s[14:15], 23
	s_add_u32 s0, s24, s0
	s_addc_u32 s1, s25, s1
	s_lshl_b32 s15, s77, 12
	s_add_u32 s0, s0, s15
	s_addc_u32 s1, s1, 0
	s_lshl_b32 s15, s2, 7
	s_add_u32 s0, s0, s15
	s_addc_u32 s1, s1, 0
	v_mov_b32_e32 v28, v37
	s_mov_b32 s15, s17
	s_mov_b32 s78, s5
